# v29 + gla3 item tail: the 8 norm-gain loads (each previously followed by vmcnt(0), which also waited for the previous block's store) issued together before the first output block
# speedup vs baseline: 1.0155x; 1.0022x over previous
; #define LAS __attribute__((address_space(3)))
; __device__ __forceinline__ f32x4 mfma16(bf16x8 colfrag, bf16x8 rowfrag, f32x4 acc) { return __builtin_amdgcn_mfma_f32_16x16x32_bf16(colfrag, rowfrag, acc, 0, 0, 0); }
; __device__ __forceinline__ float shx(float v, int lane, int o) { return __int_as_float(__builtin_amdgcn_ds_bpermute((lane ^ o) << 2, __float_as_int(v))); }
; __device__ void gla3_item(const Params& p, int l, int item, LAS unsigned char* lds) {
;     ...
;     __syncthreads();
;     bf16x8 pf[2];
; #pragma unroll
;     for (int ks = 0; ks < 2; ++ks) pf[ks] = *(const LAS bf16x8*)(hl + GL_P + (wv * 16 + fr) * 144 + (ks * 32 + fq * 8) * 2);
;     f32x4 o[8]; float ss = 0.f;
; #pragma unroll
;     for (int nt = 0; nt < 8; ++nt) { f32x4 acc = (f32x4){0.f, 0.f, 0.f, 0.f};
; #pragma unroll
;         for (int ks = 0; ks < 2; ++ks) { const bf16x8 cf = *(const LAS bf16x8*)(hl + GL_VT + (nt * 16 + fr) * 144 + (ks * 32 + fq * 8) * 2); acc = mfma16(cf, pf[ks], acc); }
;     ...
; #pragma unroll
;         for (int ks = 0; ks < 2; ++ks) acc = mfma16(spf[nt][ks], qf[ks], acc);
;     ...
;         o[nt] = acc; ss += acc[0] * acc[0] + acc[1] * acc[1] + acc[2] * acc[2] + acc[3] * acc[3]; }
;     ss += shx(ss, lane, 16); ss += shx(ss, lane, 32);
;     const float rstd = rsqrtf(ss * (1.0f / 128.0f) + EPS);
;     if (rb < TB) { const float* gn = p.gla_norm + (size_t)l * 512 + h * 128;
.LBB0_520:
	s_or_b64 exec, exec, s[10:11]
	v_cvt_pk_bf16_f32 v74, v75, v74
	v_cvt_pk_bf16_f32 v75, v78, v79
	ds_write_b64 v76, v[74:75] offset:18528
	s_waitcnt lgkmcnt(0)
	s_barrier
	ds_read_b128 v[78:81], v102 offset:18432
	ds_read_b128 v[74:77], v102 offset:18496
	ds_read_b128 v[102:105], v0 offset:27648
	ds_read_b128 v[106:109], v0 offset:27712
	s_waitcnt lgkmcnt(1)
	v_mfma_f32_16x16x32_bf16 v[102:105], v[102:105], v[78:81], 0
	s_waitcnt lgkmcnt(0)
	v_mfma_f32_16x16x32_bf16 v[102:105], v[106:109], v[74:77], v[102:105]
	v_mfma_f32_16x16x32_bf16 v[58:61], v[58:61], v[70:73], v[102:105]
	v_mfma_f32_16x16x32_bf16 v[58:61], v[62:65], v[66:69], v[58:61]
	ds_read_b128 v[62:65], v0 offset:29952
	s_nop 4
	ds_read_b128 v[102:105], v0 offset:30016
	s_waitcnt lgkmcnt(1)
	v_mfma_f32_16x16x32_bf16 v[62:65], v[62:65], v[78:81], 0
	v_mul_f32_e32 v106, v59, v59
	v_fmac_f32_e32 v106, v58, v58
	v_fmac_f32_e32 v106, v60, v60
	s_waitcnt lgkmcnt(0)
	v_mfma_f32_16x16x32_bf16 v[62:65], v[102:105], v[74:77], v[62:65]
	v_fmac_f32_e32 v106, v61, v61
	v_mfma_f32_16x16x32_bf16 v[50:53], v[50:53], v[70:73], v[62:65]
	v_mfma_f32_16x16x32_bf16 v[50:53], v[54:57], v[66:69], v[50:53]
	s_nop 4
	ds_read_b128 v[62:65], v0 offset:32320
	s_nop 1
	v_mul_f32_e32 v54, v51, v51
	v_fmac_f32_e32 v54, v50, v50
	v_fmac_f32_e32 v54, v52, v52
	v_fmac_f32_e32 v54, v53, v53
	v_add_f32_e32 v102, v106, v54
	ds_read_b128 v[54:57], v0 offset:32256
	s_waitcnt lgkmcnt(0)
	v_mfma_f32_16x16x32_bf16 v[54:57], v[54:57], v[78:81], 0
	v_mfma_f32_16x16x32_bf16 v[54:57], v[62:65], v[74:77], v[54:57]
	v_mfma_f32_16x16x32_bf16 v[46:49], v[46:49], v[70:73], v[54:57]
	v_mfma_f32_16x16x32_bf16 v[42:45], v[42:45], v[66:69], v[46:49]
	s_nop 5
	ds_read_b128 v[54:57], v0 offset:34624
	s_nop 0
	v_mul_f32_e32 v46, v43, v43
	v_fmac_f32_e32 v46, v42, v42
	v_fmac_f32_e32 v46, v44, v44
	v_fmac_f32_e32 v46, v45, v45
	v_add_f32_e32 v62, v102, v46
	ds_read_b128 v[46:49], v0 offset:34560
	s_waitcnt lgkmcnt(0)
	v_mfma_f32_16x16x32_bf16 v[46:49], v[46:49], v[78:81], 0
	v_mfma_f32_16x16x32_bf16 v[46:49], v[54:57], v[74:77], v[46:49]
	v_mfma_f32_16x16x32_bf16 v[34:37], v[34:37], v[70:73], v[46:49]
	v_mfma_f32_16x16x32_bf16 v[34:37], v[38:41], v[66:69], v[34:37]
	s_nop 5
	ds_read_b128 v[46:49], v0 offset:36928
	s_nop 0
	v_mul_f32_e32 v38, v35, v35
	v_fmac_f32_e32 v38, v34, v34
	v_fmac_f32_e32 v38, v36, v36
	v_fmac_f32_e32 v38, v37, v37
	v_add_f32_e32 v54, v62, v38
	ds_read_b128 v[38:41], v0 offset:36864
	s_waitcnt lgkmcnt(0)
	v_mfma_f32_16x16x32_bf16 v[38:41], v[38:41], v[78:81], 0
	v_mfma_f32_16x16x32_bf16 v[38:41], v[46:49], v[74:77], v[38:41]
	v_mfma_f32_16x16x32_bf16 v[26:29], v[26:29], v[70:73], v[38:41]
	v_mfma_f32_16x16x32_bf16 v[26:29], v[30:33], v[66:69], v[26:29]
	s_nop 5
	ds_read_b128 v[38:41], v0 offset:39232
	s_nop 0
	v_mul_f32_e32 v30, v27, v27
	v_fmac_f32_e32 v30, v26, v26
	v_fmac_f32_e32 v30, v28, v28
	v_fmac_f32_e32 v30, v29, v29
	v_add_f32_e32 v46, v54, v30
	ds_read_b128 v[30:33], v0 offset:39168
	s_waitcnt lgkmcnt(0)
	v_mfma_f32_16x16x32_bf16 v[30:33], v[30:33], v[78:81], 0
	v_mfma_f32_16x16x32_bf16 v[30:33], v[38:41], v[74:77], v[30:33]
	v_mfma_f32_16x16x32_bf16 v[18:21], v[18:21], v[70:73], v[30:33]
	v_mfma_f32_16x16x32_bf16 v[18:21], v[22:25], v[66:69], v[18:21]
	s_nop 5
	ds_read_b128 v[30:33], v0 offset:41536
	s_nop 0
	v_mul_f32_e32 v22, v19, v19
	v_fmac_f32_e32 v22, v18, v18
	v_fmac_f32_e32 v22, v20, v20
	v_fmac_f32_e32 v22, v21, v21
	v_add_f32_e32 v38, v46, v22
	ds_read_b128 v[22:25], v0 offset:41472
	s_waitcnt lgkmcnt(0)
	v_mfma_f32_16x16x32_bf16 v[22:25], v[22:25], v[78:81], 0
	v_mfma_f32_16x16x32_bf16 v[22:25], v[30:33], v[74:77], v[22:25]
	v_mfma_f32_16x16x32_bf16 v[10:13], v[10:13], v[70:73], v[22:25]
	v_mfma_f32_16x16x32_bf16 v[10:13], v[14:17], v[66:69], v[10:13]
	s_nop 5
	ds_read_b128 v[22:25], v0 offset:43840
	s_nop 0
	v_mul_f32_e32 v14, v11, v11
	v_fmac_f32_e32 v14, v10, v10
	v_fmac_f32_e32 v14, v12, v12
	v_fmac_f32_e32 v14, v13, v13
	v_add_f32_e32 v30, v38, v14
	ds_read_b128 v[14:17], v0 offset:43776
	s_waitcnt lgkmcnt(0)
	v_mfma_f32_16x16x32_bf16 v[14:17], v[14:17], v[78:81], 0
	v_mfma_f32_16x16x32_bf16 v[14:17], v[22:25], v[74:77], v[14:17]
	v_mfma_f32_16x16x32_bf16 v[6:9], v[6:9], v[70:73], v[14:17]
	v_mfma_f32_16x16x32_bf16 v[2:5], v[2:5], v[66:69], v[6:9]
	s_nop 6
	v_xor_b32_e32 v6, 64, v100
	v_mul_f32_e32 v0, v3, v3
	v_fmac_f32_e32 v0, v2, v2
	v_fmac_f32_e32 v0, v4, v4
	v_fmac_f32_e32 v0, v5, v5
	v_add_f32_e32 v0, v30, v0
	ds_bpermute_b32 v6, v6, v0
	s_waitcnt lgkmcnt(0)
	v_add_f32_e32 v0, v0, v6
	v_xor_b32_e32 v6, 0x80, v100
	ds_bpermute_b32 v6, v6, v0
	s_and_saveexec_b64 s[10:11], vcc
	s_cbranch_execz .LBB0_522
; __device__ __forceinline__ float bflo(unsigned w) { return __uint_as_float(w << 16); }
; __device__ __forceinline__ float bfhi(unsigned w) { return __uint_as_float(w & 0xffff0000u); }
; __device__ __forceinline__ unsigned cvt_pk_bf16(float lo, float hi) { const f32x2 f = {lo, hi}; const bf16n2 v = __builtin_convertvector(f, bf16n2); return __builtin_bit_cast(unsigned, v); }
; __device__ __forceinline__ float siluf_(float x) { return x * sigmoidf_(x); }
; __device__ void gla3_item(const Params& p, int l, int item, LAS unsigned char* lds) {
;     ...
;     const float rstd = rsqrtf(ss * (1.0f / 128.0f) + EPS);
;     if (rb < TB) { const float* gn = p.gla_norm + (size_t)l * 512 + h * 128;
; #pragma unroll
;         for (int nt = 0; nt < 8; ++nt) { const int dv = nt * 16 + 4 * fq; const f32x4 gv = *(const f32x4*)(gn + dv); const u32x2 rw = rwv[nt];
;             const float v0 = o[nt][0] * rstd * gv[0] * siluf_(bflo(rw.x)), v1 = o[nt][1] * rstd * gv[1] * siluf_(bfhi(rw.x)),
;                         v2 = o[nt][2] * rstd * gv[2] * siluf_(bflo(rw.y)), v3 = o[nt][3] * rstd * gv[3] * siluf_(bfhi(rw.y));
;             u32x2 w; w.x = cvt_pk_bf16(v0, v1); w.y = cvt_pk_bf16(v2, v3); if (!p.dry) *(u32x2*)(rowp + C_V + h * 128 + dv) = w; } }
	s_waitcnt lgkmcnt(0)
	v_add_f32_e32 v0, v0, v6
	v_fmamk_f32 v0, v0, 0x3c000000, v229
	s_mov_b32 s15, 0x800000
	v_cmp_gt_f32_e32 vcc, s15, v0
	v_mul_f32_e32 v6, 0x4b800000, v0
	s_lshl_b32 s14, s14, 2
	v_cndmask_b32_e32 v0, v0, v6, vcc
	v_rsq_f32_e32 v0, v0
	s_add_u32 s40, s19, s14
	s_addc_u32 s41, s72, 0
	v_lshlrev_b32_e32 v8, 16, v98
	v_mul_f32_e32 v6, 0x45800000, v0
	v_cndmask_b32_e32 v0, v0, v6, vcc
	v_lshlrev_b32_e32 v6, 2, v101
	global_load_dwordx4 v[204:207], v6, s[40:41]
	global_load_dwordx4 v[208:211], v6, s[40:41] offset:64
	global_load_dwordx4 v[212:215], v6, s[40:41] offset:128
	global_load_dwordx4 v[216:219], v6, s[40:41] offset:192
	global_load_dwordx4 v[220:223], v6, s[40:41] offset:256
	global_load_dwordx4 v[224:227], v6, s[40:41] offset:320
	global_load_dwordx4 v[240:243], v6, s[40:41] offset:384
	global_load_dwordx4 v[244:247], v6, s[40:41] offset:448
	v_mul_f32_e32 v7, 0xbfb8aa3b, v8
	v_exp_f32_e32 v7, v7
	v_and_b32_e32 v9, 0xffff0000, v98
	v_pk_mul_f32 v[24:25], v[58:59], v[0:1] op_sel_hi:[1,0]
	v_pk_mul_f32 v[18:19], v[18:19], v[0:1] op_sel_hi:[1,0]
	v_add_f32_e32 v7, 1.0, v7
	v_rcp_f32_e32 v22, v7
	v_mul_f32_e32 v7, 0xbfb8aa3b, v9
	v_exp_f32_e32 v7, v7
	v_pk_mul_f32 v[20:21], v[20:21], v[0:1] op_sel_hi:[1,0]
	v_pk_mul_f32 v[10:11], v[10:11], v[0:1] op_sel_hi:[1,0]
	v_pk_mul_f32 v[12:13], v[12:13], v[0:1] op_sel_hi:[1,0]
	v_add_f32_e32 v7, 1.0, v7
	v_rcp_f32_e32 v23, v7
	v_pk_mul_f32 v[2:3], v[2:3], v[0:1] op_sel_hi:[1,0]
	v_pk_mul_f32 v[4:5], v[4:5], v[0:1] op_sel_hi:[1,0]
	v_pk_mul_f32 v[8:9], v[22:23], v[8:9]
	s_waitcnt vmcnt(0)
	v_pk_mul_f32 v[14:15], v[24:25], v[204:205]
	s_nop 0
	v_pk_mul_f32 v[8:9], v[8:9], v[14:15]
	v_lshlrev_b32_e32 v14, 16, v99
	v_mul_f32_e32 v7, 0xbfb8aa3b, v14
	v_exp_f32_e32 v7, v7
	v_and_b32_e32 v15, 0xffff0000, v99
	v_pk_mul_f32 v[24:25], v[60:61], v[0:1] op_sel_hi:[1,0]
	v_cvt_pk_bf16_f32 v8, v8, v9
	v_add_f32_e32 v7, 1.0, v7
	v_rcp_f32_e32 v22, v7
	v_mul_f32_e32 v7, 0xbfb8aa3b, v15
	v_exp_f32_e32 v7, v7
	v_pk_mul_f32 v[16:17], v[24:25], v[206:207]
	v_pk_mul_f32 v[24:25], v[50:51], v[0:1] op_sel_hi:[1,0]
	v_add_f32_e32 v7, 1.0, v7
	v_rcp_f32_e32 v23, v7
	s_nop 0
	v_pk_mul_f32 v[14:15], v[22:23], v[14:15]
	s_nop 0
	v_pk_mul_f32 v[14:15], v[14:15], v[16:17]
	s_nop 0
	v_cvt_pk_bf16_f32 v9, v14, v15
	global_store_dwordx2 v[82:83], v[8:9], off offset:2048
	v_lshlrev_b32_e32 v8, 16, v96
	v_mul_f32_e32 v7, 0xbfb8aa3b, v8
	v_exp_f32_e32 v7, v7
	v_and_b32_e32 v9, 0xffff0000, v96
	v_add_f32_e32 v7, 1.0, v7
	v_rcp_f32_e32 v22, v7
	v_mul_f32_e32 v7, 0xbfb8aa3b, v9
	v_exp_f32_e32 v7, v7
	v_pk_mul_f32 v[14:15], v[24:25], v[208:209]
	v_add_f32_e32 v7, 1.0, v7
	v_rcp_f32_e32 v23, v7
	v_pk_mul_f32 v[24:25], v[52:53], v[0:1] op_sel_hi:[1,0]
	v_pk_mul_f32 v[8:9], v[22:23], v[8:9]
	s_nop 0
	v_pk_mul_f32 v[8:9], v[8:9], v[14:15]
	v_lshlrev_b32_e32 v14, 16, v97
	v_mul_f32_e32 v7, 0xbfb8aa3b, v14
	v_exp_f32_e32 v7, v7
	v_and_b32_e32 v15, 0xffff0000, v97
	v_pk_mul_f32 v[16:17], v[24:25], v[210:211]
	v_cvt_pk_bf16_f32 v8, v8, v9
	v_add_f32_e32 v7, 1.0, v7
	v_rcp_f32_e32 v22, v7
	v_mul_f32_e32 v7, 0xbfb8aa3b, v15
	v_exp_f32_e32 v7, v7
	v_pk_mul_f32 v[24:25], v[42:43], v[0:1] op_sel_hi:[1,0]
	v_add_f32_e32 v7, 1.0, v7
	v_rcp_f32_e32 v23, v7
	s_nop 0
	v_pk_mul_f32 v[14:15], v[22:23], v[14:15]
	s_nop 0
	v_pk_mul_f32 v[14:15], v[14:15], v[16:17]
	s_nop 0
	v_cvt_pk_bf16_f32 v9, v14, v15
	global_store_dwordx2 v[82:83], v[8:9], off offset:2080
	v_lshlrev_b32_e32 v8, 16, v94
	v_mul_f32_e32 v7, 0xbfb8aa3b, v8
	v_exp_f32_e32 v7, v7
	v_and_b32_e32 v9, 0xffff0000, v94
	v_add_f32_e32 v7, 1.0, v7
	v_rcp_f32_e32 v22, v7
	v_mul_f32_e32 v7, 0xbfb8aa3b, v9
	v_exp_f32_e32 v7, v7
	v_pk_mul_f32 v[14:15], v[24:25], v[212:213]
	v_add_f32_e32 v7, 1.0, v7
	v_rcp_f32_e32 v23, v7
	v_pk_mul_f32 v[24:25], v[44:45], v[0:1] op_sel_hi:[1,0]
	v_pk_mul_f32 v[8:9], v[22:23], v[8:9]
	s_nop 0
	v_pk_mul_f32 v[8:9], v[8:9], v[14:15]
	v_lshlrev_b32_e32 v14, 16, v95
	v_mul_f32_e32 v7, 0xbfb8aa3b, v14
	v_exp_f32_e32 v7, v7
	v_and_b32_e32 v15, 0xffff0000, v95
	v_pk_mul_f32 v[16:17], v[24:25], v[214:215]
	v_cvt_pk_bf16_f32 v8, v8, v9
	v_add_f32_e32 v7, 1.0, v7
	v_rcp_f32_e32 v22, v7
	v_mul_f32_e32 v7, 0xbfb8aa3b, v15
	v_exp_f32_e32 v7, v7
	v_pk_mul_f32 v[24:25], v[34:35], v[0:1] op_sel_hi:[1,0]
	v_add_f32_e32 v7, 1.0, v7
	v_rcp_f32_e32 v23, v7
	s_nop 0
	v_pk_mul_f32 v[14:15], v[22:23], v[14:15]
	s_nop 0
	v_pk_mul_f32 v[14:15], v[14:15], v[16:17]
	s_nop 0
	v_cvt_pk_bf16_f32 v9, v14, v15
	global_store_dwordx2 v[82:83], v[8:9], off offset:2112
	v_lshlrev_b32_e32 v8, 16, v92
	v_mul_f32_e32 v7, 0xbfb8aa3b, v8
	v_exp_f32_e32 v7, v7
	v_and_b32_e32 v9, 0xffff0000, v92
	v_add_f32_e32 v7, 1.0, v7
	v_rcp_f32_e32 v22, v7
	v_mul_f32_e32 v7, 0xbfb8aa3b, v9
	v_exp_f32_e32 v7, v7
	v_pk_mul_f32 v[14:15], v[24:25], v[216:217]
; __device__ __forceinline__ float bflo(unsigned w) { return __uint_as_float(w << 16); }
; __device__ __forceinline__ float bfhi(unsigned w) { return __uint_as_float(w & 0xffff0000u); }
; __device__ __forceinline__ unsigned cvt_pk_bf16(float lo, float hi) { const f32x2 f = {lo, hi}; const bf16n2 v = __builtin_convertvector(f, bf16n2); return __builtin_bit_cast(unsigned, v); }
; __device__ __forceinline__ float siluf_(float x) { return x * sigmoidf_(x); }
; __device__ void gla3_item(const Params& p, int l, int item, LAS unsigned char* lds) {
;     ...
;     const float rstd = rsqrtf(ss * (1.0f / 128.0f) + EPS);
;     if (rb < TB) { const float* gn = p.gla_norm + (size_t)l * 512 + h * 128;
; #pragma unroll
;         for (int nt = 0; nt < 8; ++nt) { const int dv = nt * 16 + 4 * fq; const f32x4 gv = *(const f32x4*)(gn + dv); const u32x2 rw = rwv[nt];
;             const float v0 = o[nt][0] * rstd * gv[0] * siluf_(bflo(rw.x)), v1 = o[nt][1] * rstd * gv[1] * siluf_(bfhi(rw.x)),
;                         v2 = o[nt][2] * rstd * gv[2] * siluf_(bflo(rw.y)), v3 = o[nt][3] * rstd * gv[3] * siluf_(bfhi(rw.y));
;             u32x2 w; w.x = cvt_pk_bf16(v0, v1); w.y = cvt_pk_bf16(v2, v3); if (!p.dry) *(u32x2*)(rowp + C_V + h * 128 + dv) = w; } }
	v_add_f32_e32 v7, 1.0, v7
	v_rcp_f32_e32 v23, v7
	v_pk_mul_f32 v[24:25], v[36:37], v[0:1] op_sel_hi:[1,0]
	v_pk_mul_f32 v[8:9], v[22:23], v[8:9]
	s_nop 0
	v_pk_mul_f32 v[8:9], v[8:9], v[14:15]
	v_lshlrev_b32_e32 v14, 16, v93
	v_mul_f32_e32 v7, 0xbfb8aa3b, v14
	v_exp_f32_e32 v7, v7
	v_and_b32_e32 v15, 0xffff0000, v93
	v_pk_mul_f32 v[16:17], v[24:25], v[218:219]
	v_cvt_pk_bf16_f32 v8, v8, v9
	v_add_f32_e32 v7, 1.0, v7
	v_rcp_f32_e32 v22, v7
	v_mul_f32_e32 v7, 0xbfb8aa3b, v15
	v_exp_f32_e32 v7, v7
	v_pk_mul_f32 v[24:25], v[26:27], v[0:1] op_sel_hi:[1,0]
	v_add_f32_e32 v7, 1.0, v7
	v_rcp_f32_e32 v23, v7
	s_nop 0
	v_pk_mul_f32 v[14:15], v[22:23], v[14:15]
	s_nop 0
	v_pk_mul_f32 v[14:15], v[14:15], v[16:17]
	s_nop 0
	v_cvt_pk_bf16_f32 v9, v14, v15
	global_store_dwordx2 v[82:83], v[8:9], off offset:2144
	v_lshlrev_b32_e32 v8, 16, v90
	v_mul_f32_e32 v7, 0xbfb8aa3b, v8
	v_exp_f32_e32 v7, v7
	v_and_b32_e32 v9, 0xffff0000, v90
	v_add_f32_e32 v7, 1.0, v7
	v_rcp_f32_e32 v22, v7
	v_mul_f32_e32 v7, 0xbfb8aa3b, v9
	v_exp_f32_e32 v7, v7
	v_pk_mul_f32 v[14:15], v[24:25], v[220:221]
	v_add_f32_e32 v7, 1.0, v7
	v_rcp_f32_e32 v23, v7
	v_pk_mul_f32 v[24:25], v[28:29], v[0:1] op_sel_hi:[1,0]
	v_pk_mul_f32 v[8:9], v[22:23], v[8:9]
	s_nop 0
	v_pk_mul_f32 v[8:9], v[8:9], v[14:15]
	v_lshlrev_b32_e32 v14, 16, v91
	v_mul_f32_e32 v7, 0xbfb8aa3b, v14
	v_exp_f32_e32 v7, v7
	v_and_b32_e32 v15, 0xffff0000, v91
	v_pk_mul_f32 v[16:17], v[24:25], v[222:223]
	v_cvt_pk_bf16_f32 v8, v8, v9
	v_add_f32_e32 v7, 1.0, v7
	v_rcp_f32_e32 v22, v7
	v_mul_f32_e32 v7, 0xbfb8aa3b, v15
	v_exp_f32_e32 v7, v7
	s_nop 0
	v_add_f32_e32 v7, 1.0, v7
	v_rcp_f32_e32 v23, v7
	s_nop 0
	v_pk_mul_f32 v[14:15], v[22:23], v[14:15]
	s_nop 0
	v_pk_mul_f32 v[14:15], v[14:15], v[16:17]
	s_nop 0
	v_cvt_pk_bf16_f32 v9, v14, v15
	global_store_dwordx2 v[82:83], v[8:9], off offset:2176
	v_lshlrev_b32_e32 v8, 16, v88
	v_mul_f32_e32 v7, 0xbfb8aa3b, v8
	v_exp_f32_e32 v7, v7
	v_and_b32_e32 v9, 0xffff0000, v88
	v_add_f32_e32 v7, 1.0, v7
	v_rcp_f32_e32 v22, v7
	v_mul_f32_e32 v7, 0xbfb8aa3b, v9
	v_exp_f32_e32 v7, v7
	v_pk_mul_f32 v[14:15], v[18:19], v[224:225]
	v_add_f32_e32 v7, 1.0, v7
	v_rcp_f32_e32 v23, v7
	v_pk_mul_f32 v[16:17], v[20:21], v[226:227]
	v_pk_mul_f32 v[8:9], v[22:23], v[8:9]
	s_nop 0
	v_pk_mul_f32 v[8:9], v[8:9], v[14:15]
	v_lshlrev_b32_e32 v14, 16, v89
	v_mul_f32_e32 v7, 0xbfb8aa3b, v14
	v_exp_f32_e32 v7, v7
	v_and_b32_e32 v15, 0xffff0000, v89
	v_cvt_pk_bf16_f32 v8, v8, v9
	v_add_f32_e32 v7, 1.0, v7
	v_rcp_f32_e32 v18, v7
	v_mul_f32_e32 v7, 0xbfb8aa3b, v15
	v_exp_f32_e32 v7, v7
	s_nop 0
	v_add_f32_e32 v7, 1.0, v7
	v_rcp_f32_e32 v19, v7
	s_nop 0
	v_pk_mul_f32 v[14:15], v[18:19], v[14:15]
	s_nop 0
	v_pk_mul_f32 v[14:15], v[14:15], v[16:17]
	s_nop 0
	v_cvt_pk_bf16_f32 v9, v14, v15
	global_store_dwordx2 v[82:83], v[8:9], off offset:2208
	v_lshlrev_b32_e32 v8, 16, v86
	v_mul_f32_e32 v7, 0xbfb8aa3b, v8
	v_exp_f32_e32 v7, v7
	v_and_b32_e32 v9, 0xffff0000, v86
	v_add_f32_e32 v7, 1.0, v7
	v_rcp_f32_e32 v18, v7
	v_mul_f32_e32 v7, 0xbfb8aa3b, v9
	v_exp_f32_e32 v7, v7
	v_pk_mul_f32 v[10:11], v[10:11], v[240:241]
	v_add_f32_e32 v7, 1.0, v7
	v_rcp_f32_e32 v19, v7
	v_pk_mul_f32 v[12:13], v[12:13], v[242:243]
	v_pk_mul_f32 v[8:9], v[18:19], v[8:9]
	s_nop 0
	v_pk_mul_f32 v[8:9], v[8:9], v[10:11]
	v_lshlrev_b32_e32 v10, 16, v87
	v_mul_f32_e32 v7, 0xbfb8aa3b, v10
	v_exp_f32_e32 v7, v7
	v_and_b32_e32 v11, 0xffff0000, v87
	v_cvt_pk_bf16_f32 v8, v8, v9
	v_add_f32_e32 v7, 1.0, v7
	v_rcp_f32_e32 v14, v7
	v_mul_f32_e32 v7, 0xbfb8aa3b, v11
	v_exp_f32_e32 v7, v7
	s_nop 0
	v_add_f32_e32 v7, 1.0, v7
	v_rcp_f32_e32 v15, v7
	s_nop 0
	v_pk_mul_f32 v[10:11], v[14:15], v[10:11]
	s_nop 0
	v_pk_mul_f32 v[10:11], v[10:11], v[12:13]
	s_nop 0
	v_cvt_pk_bf16_f32 v9, v10, v11
	global_store_dwordx2 v[82:83], v[8:9], off offset:2240
	v_lshlrev_b32_e32 v10, 16, v84
	v_and_b32_e32 v11, 0xffff0000, v84
	v_mul_f32_e32 v12, 0xbfb8aa3b, v10
	v_exp_f32_e32 v12, v12
	v_pk_mul_f32 v[2:3], v[2:3], v[244:245]
	v_mul_f32_e32 v6, 0xbfb8aa3b, v11
	v_exp_f32_e32 v6, v6
	v_add_f32_e32 v12, 1.0, v12
	v_rcp_f32_e32 v12, v12
	v_pk_mul_f32 v[4:5], v[4:5], v[246:247]
	v_add_f32_e32 v6, 1.0, v6
	v_rcp_f32_e32 v13, v6
	s_nop 0
	v_pk_mul_f32 v[6:7], v[12:13], v[10:11]
	s_nop 0
	v_pk_mul_f32 v[2:3], v[6:7], v[2:3]
	v_lshlrev_b32_e32 v6, 16, v85
	v_and_b32_e32 v7, 0xffff0000, v85
	v_cvt_pk_bf16_f32 v2, v2, v3
	v_mul_f32_e32 v3, 0xbfb8aa3b, v6
	v_mul_f32_e32 v0, 0xbfb8aa3b, v7
	v_exp_f32_e32 v3, v3
	v_exp_f32_e32 v0, v0
	v_add_f32_e32 v3, 1.0, v3
	v_add_f32_e32 v0, 1.0, v0
	v_rcp_f32_e32 v10, v3
	v_rcp_f32_e32 v11, v0
	s_nop 0
	v_pk_mul_f32 v[6:7], v[10:11], v[6:7]
	s_nop 0
	v_pk_mul_f32 v[4:5], v[6:7], v[4:5]
	s_nop 0
	v_cvt_pk_bf16_f32 v3, v4, v5
	global_store_dwordx2 v[82:83], v[2:3], off offset:2272
